# sequence-aligned XCD ownership (XCD x: ctx tiles 2x,2x+1 + latent tiles 16+4x..19+4x) for out-proj/ff1/ff2, mixer queue without cross-XCD stealing and with per-XCD deferred-tile head, XCD-local barrie
# speedup vs baseline: 1.0259x; 1.0186x over previous
.Lmy_rank_skip:
	s_or_b64 exec, exec, s[60:61]
	s_waitcnt vmcnt(0) lgkmcnt(0)
	s_barrier
	v_mov_b32_e32 v1, 0x20040
	ds_read_b32 v1, v1
	v_readfirstlane_b32 s58, v0
	s_waitcnt lgkmcnt(0)
	v_readfirstlane_b32 s59, v1
	s_lshl_b32 s59, s59, 3
	s_add_i32 s59, s59, s71
	s_cmp_eq_u32 s58, 0
	s_cselect_b32 s2, s59, s2
	s_cselect_b32 s58, 1, 0
	s_nop 0
	v_writelane_b32 v255, s58, 46
	s_ashr_i32 s43, s2, 31
	s_lshr_b32 s0, s43, 29
	s_add_i32 s0, s2, s0
	s_and_b32 s1, s0, -8
	s_sub_i32 s1, s2, s1
	s_add_i32 s4, s76, 0xfffffa00
	s_cmp_lt_i32 s1, 0
	s_movk_i32 s7, 0x61
	s_cselect_b32 s5, 45, 44
	s_cselect_b32 s6, 25, 24
	s_cselect_b32 s7, s7, 0x60
	s_cmpk_gt_i32 s42, 0xc0
	s_cselect_b32 s33, s4, s76
	s_add_i32 s4, s42, 0xffffff40
	s_cmpk_gt_i32 s42, 0xc0
	s_cselect_b32 s63, s4, s42
	s_add_i32 s4, s2, 0xffffff40
	s_mov_b32 s8, s76
	s_cmpk_gt_i32 s42, 0xc0
	v_writelane_b32 v254, s8, 17
	s_cselect_b32 s13, s4, s2
	s_cmpk_lt_i32 s2, 0x200
	v_writelane_b32 v254, s9, 18
	s_cselect_b64 s[8:9], -1, 0
	v_writelane_b32 v254, s8, 19
	s_add_i32 s4, s2, 0xa0
	s_bfe_u32 s4, s4, 0x50003
	v_writelane_b32 v254, s9, 20
	s_and_b32 s8, s2, 7
	s_mul_i32 s8, s8, 20
	s_add_i32 s4, s4, s8
	s_mul_i32 s8, s4, 0xcd
	s_bfe_u32 s8, s8, 0x3000d
	s_mul_i32 s9, s8, 40
	s_mul_i32 s5, s5, s1
	s_sub_i32 s9, s4, s9
	s_ashr_i32 s4, s0, 3
	s_add_i32 s5, s5, s4
	s_mul_hi_i32 s0, s5, 0x2e8ba2e9
	s_lshr_b32 s11, s0, 31
	s_ashr_i32 s0, s0, 4
	s_add_i32 s0, s0, s11
	s_mul_i32 s11, s0, 0x58
	s_sub_i32 s5, s5, s11
	s_bfe_i32 s11, s5, 0x80000
	s_bfe_u32 s11, s11, 0x3000c
	s_add_i32 s11, s5, s11
	s_bfe_i32 s12, s11, 0x80000
	s_and_b32 s11, s11, 0xf8
	s_lshl_b32 s8, s8, 2
	s_sub_i32 s5, s5, s11
	s_and_b32 s10, s8, 28
	s_lshl_b32 s0, s0, 3
	s_sext_i32_i8 s5, s5
	s_sub_i32 s10, 16, s10
	s_sext_i32_i16 s12, s12
	s_add_i32 s0, s0, s5
	s_min_u32 s10, s10, 4
	s_ashr_i32 s11, s12, 3
	s_add_i32 s0, s0, 16
	s_ashr_i32 s51, s42, 31
	s_add_u32 s48, s38, 0x4820000
	s_addc_u32 s49, s39, 0
	s_add_u32 s50, s38, 0x3820000
	s_addc_u32 s68, s39, 0
	s_add_u32 s69, s38, 0x5820000
	s_addc_u32 s62, s39, 0
	v_writelane_b32 v254, s11, 21
	s_add_u32 s14, s40, 0x4200
	v_writelane_b32 v254, s0, 22
	s_addc_u32 s15, s41, 0
	v_writelane_b32 v254, s14, 23
	s_waitcnt lgkmcnt(0)
	v_cvt_f32_ubyte0_e32 v0, s10
	v_rcp_iflag_f32_e32 v1, v0
	v_writelane_b32 v254, s15, 24
	s_add_u32 s14, s40, 0x7400
	s_addc_u32 s15, s41, 0
	v_writelane_b32 v254, s14, 25
	v_cvt_f32_ubyte0_e32 v2, s9
	v_mul_f32_e32 v1, v2, v1
	v_writelane_b32 v254, s15, 26
	s_add_u32 s14, s40, 0x7500
	s_addc_u32 s15, s41, 0
	v_writelane_b32 v254, s14, 27
	s_add_u32 s0, s40, 0x2000
	v_trunc_f32_e32 v1, v1
	v_writelane_b32 v254, s15, 28
	v_writelane_b32 v254, s0, 29
	s_addc_u32 s0, s41, 0
	s_cmpk_lt_i32 s2, 0xc0
	v_writelane_b32 v254, s0, 30
	s_cselect_b64 s[14:15], -1, 0
	v_writelane_b32 v254, s14, 31
	s_cmp_lt_i32 s13, 0
	v_cvt_u32_f32_e32 v3, v1
	v_writelane_b32 v254, s15, 32
	s_cselect_b64 s[14:15], -1, 0
	v_writelane_b32 v254, s14, 33
	s_cmpk_lt_u32 s13, 0x6c
	v_fma_f32 v1, -v1, v0, v2
	v_writelane_b32 v254, s15, 34
	s_cselect_b64 s[14:15], -1, 0
	v_writelane_b32 v254, s14, 35
	s_add_u32 s0, s40, 0x400000
	s_mov_b32 s97, 0
	v_writelane_b32 v254, s15, 36
	v_writelane_b32 v254, s0, 37
	s_addc_u32 s0, s41, 0
	v_writelane_b32 v254, s0, 38
	s_add_u32 s0, s40, 0x300000
	v_writelane_b32 v254, s0, 39
	s_addc_u32 s0, s41, 0
	s_cmpk_lt_i32 s2, 0x300
	v_writelane_b32 v254, s0, 40
	s_cselect_b64 s[14:15], -1, 0
	v_writelane_b32 v254, s14, 41
	s_lshl_b32 s0, s13, 3
	v_mov_b32_e32 v65, 0
	v_writelane_b32 v254, s15, 42
	v_writelane_b32 v254, s0, 43
	s_add_u32 s0, s40, 0x4600000
	v_writelane_b32 v254, s0, 44
	s_addc_u32 s0, s41, 0
	v_writelane_b32 v254, s0, 45
	s_add_u32 s0, s40, 0x2600000
	v_writelane_b32 v254, s0, 46
	s_addc_u32 s0, s41, 0
	v_writelane_b32 v254, s0, 47
	s_add_u32 s0, s40, 0x1e00000
	v_writelane_b32 v254, s0, 48
	s_addc_u32 s0, s41, 0
	v_writelane_b32 v254, s0, 49
	s_add_u32 s0, s40, 0x800000
	v_writelane_b32 v254, s0, 50
	s_addc_u32 s0, s41, 0
	v_writelane_b32 v254, s0, 51
	s_add_i32 s0, s2, 0xfffffe00
	s_cmp_gt_u32 s0, 0xffffff5f
	s_mul_i32 s0, s1, s6
	s_cselect_b64 s[14:15], -1, 0
	s_add_i32 s0, s0, s4
	s_ashr_i32 s5, s0, 31
	s_lshr_b32 s5, s5, 27
	s_add_i32 s5, s0, s5
	s_ashr_i32 s6, s5, 5
	s_and_b32 s5, s5, 0xffe0
	s_sub_i32 s5, s0, s5
	s_bfe_i32 s0, s5, 0x80000
	s_bfe_u32 s0, s0, 0x3000c
	s_add_i32 s11, s5, s0
	s_mul_i32 s1, s1, s7
	s_bfe_i32 s0, s11, 0x80000
	s_and_b32 s11, s11, 0xf8
	s_add_i32 s1, s1, s4
	s_sub_i32 s5, s5, s11
	s_ashr_i32 s4, s1, 31
	v_writelane_b32 v254, s14, 52
	s_lshl_b32 s6, s6, 3
	s_sext_i32_i16 s12, s0
	s_sext_i32_i8 s5, s5
	s_lshr_b32 s4, s4, 25
	v_writelane_b32 v254, s15, 53
	s_add_i32 s14, s6, s5
	s_ashr_i32 s5, s12, 3
	s_add_i32 s4, s1, s4
	v_writelane_b32 v254, s5, 54
	s_ashr_i32 s5, s4, 7
	s_and_b32 s4, s4, 0xff80
	s_sub_i32 s1, s1, s4
	s_bfe_i32 s4, s1, 0x80000
	s_bfe_u32 s4, s4, 0x3000c
	s_add_i32 s6, s1, s4
	s_bfe_i32 s4, s6, 0x80000
	s_and_b32 s6, s6, 0xf8
	s_sub_i32 s1, s1, s6
	s_lshl_b32 s5, s5, 3
	s_sext_i32_i16 s7, s4
	s_sext_i32_i8 s1, s1
	s_add_i32 s16, s5, s1
	s_ashr_i32 s1, s7, 3
	v_writelane_b32 v254, s1, 55
	s_mov_b32 s6, s16
	s_lshr_b32 s4, s7, 3
	s_ashr_i32 s17, s16, 31
	v_writelane_b32 v254, s6, 56
	s_bfe_i64 s[4:5], s[4:5], 0x100000
	s_lshl_b64 s[4:5], s[4:5], 19
	v_writelane_b32 v254, s7, 57
	s_lshl_b64 s[6:7], s[16:17], 19
	v_writelane_b32 v254, s6, 58
	s_ashr_i32 s15, s14, 31
	s_lshr_b32 s0, s12, 3
	v_writelane_b32 v254, s7, 59
	v_writelane_b32 v254, s4, 60
	s_bfe_i64 s[0:1], s[0:1], 0x100000
	v_mov_b32_e32 v229, 0x358637bd
	v_writelane_b32 v254, s5, 61
	s_lshl_b64 s[4:5], s[14:15], 19
	v_writelane_b32 v254, s4, 62
	v_mov_b32_e32 v230, 1
	v_mov_b32_e32 v190, 0x3f4ccccd
	v_writelane_b32 v254, s5, 63
	s_lshl_b64 s[4:5], s[0:1], 19
	v_writelane_b32 v255, s4, 0
	s_lshl_b64 s[0:1], s[0:1], 21
	v_mov_b32_e32 v231, 0x1000
	v_writelane_b32 v255, s5, 1
	s_mov_b32 s4, s14
	v_writelane_b32 v255, s4, 2
	v_mov_b32_e32 v232, 0x3ecc95a3
	v_mov_b32_e32 v233, 0x3c088889
	v_writelane_b32 v255, s5, 3
	s_lshl_b64 s[4:5], s[14:15], 21
	v_writelane_b32 v255, s4, 4
	v_mov_b32_e32 v234, 0x7f800000
	v_mov_b32_e32 v235, 0x7fc00000
	v_writelane_b32 v255, s5, 5
	v_writelane_b32 v255, s0, 6
	v_readfirstlane_b32 s4, v3
	v_mov_b32_e32 v236, 0xff800000
	v_writelane_b32 v255, s1, 7
	v_cmp_ge_f32_e64 s[0:1], |v1|, v0
	s_cmp_lg_u64 s[0:1], 0
	s_addc_u32 s0, s4, 0
	s_mul_i32 s1, s0, s10
	s_sub_i32 s1, s9, s1
	s_add_i32 s1, s1, s8
	s_and_b32 s1, s1, 0xff
	s_and_b32 s4, s0, 0xff
	s_cmp_gt_u32 s4, 7
	v_writelane_b32 v255, s1, 8
	s_cselect_b64 s[0:1], -1, 0
	s_cmp_lg_u64 s[0:1], 0
	s_addc_u32 s0, s4, 0
	s_load_dwordx8 s[4:11], s[80:81], 0xd0
	v_writelane_b32 v255, s0, 9
	v_writelane_b32 v255, s13, 10
	s_lshl_b32 s0, s13, 6
	v_writelane_b32 v255, s0, 11
	s_addk_i32 s0, 0xf500
	s_lshl_b32 s79, s63, 6
	s_waitcnt lgkmcnt(0)
	s_mov_b64 s[4:5], s[8:9]
	v_writelane_b32 v255, s0, 12
	s_add_u32 s0, s4, 0x1000000
	s_addc_u32 s1, s5, 0
	v_writelane_b32 v255, s0, 13
	v_mov_b32_e32 v237, 0x3e800000
	v_bfrev_b32_e32 v238, 0.5
	v_writelane_b32 v255, s1, 14
	s_load_dwordx2 s[0:1], s[80:81], 0x68
	v_mov_b64_e32 v[192:193], 0xc0
	v_mov_b64_e32 v[194:195], 0xbf
	v_not_b32_e32 v239, 30
	s_mov_b32 s55, 0x800000
	s_waitcnt lgkmcnt(0)
	s_add_u32 s0, s0, 0xb00000
	s_addc_u32 s1, s1, 0
	v_writelane_b32 v255, s0, 15
	s_movk_i32 s92, 0x3ff
	s_movk_i32 s93, 0x1600
	v_writelane_b32 v255, s1, 16
	s_add_i32 s0, 0, 0x20020
	v_writelane_b32 v255, s0, 17
	s_add_i32 s0, 0, 0x20024
	v_writelane_b32 v255, s0, 18
	s_add_i32 s0, 0, 0x12200
	v_writelane_b32 v255, s0, 19
	s_add_i32 s0, 0, 0x15800
	v_writelane_b32 v255, s0, 20
	s_brev_b32 s0, 1
	v_writelane_b32 v255, s0, 21
	s_movk_i32 s94, 0x90
	s_movk_i32 s95, 0xf7
	v_writelane_b32 v255, s1, 22
	v_writelane_b32 v255, s2, 23
	v_writelane_b32 v255, s3, 24
	v_writelane_b32 v255, s80, 25
	s_movk_i32 s46, 0x7d0
	s_add_i32 s47, 0, 0x20000
	v_writelane_b32 v255, s81, 26
	v_writelane_b32 v255, s63, 27
	v_writelane_b32 v255, s79, 28
	s_mov_b32 s52, 0x41000000
	s_movk_i32 s54, 0xfeff
	s_mov_b32 s64, 0xc800
	s_mov_b32 s65, 0xbe800000
	s_movk_i32 s78, 0x2c00
	s_mov_b64 s[28:29], 0
	s_mov_b64 s[30:31], 0x80
	s_mov_b64 s[72:73], 0
	s_mov_b32 s74, s97
	s_and_b32 s58, s2, 7
	s_lshr_b32 s59, s2, 3
	s_mul_i32 s60, s59, 43
	s_lshr_b32 s60, s60, 8
	s_mul_i32 s61, s60, 6
	s_sub_i32 s59, s59, s61
	s_lshl_b32 s61, s58, 1
	s_add_i32 s61, s61, s59
	s_lshl_b32 s58, s58, 2
	s_add_i32 s58, s58, s59
	s_add_i32 s58, s58, 14
	s_cmp_lt_u32 s59, 2
	s_cselect_b32 s58, s61, s58
	s_mov_b32 s61, 0
	v_writelane_b32 v254, s60, 54
	v_writelane_b32 v254, s60, 55
	v_writelane_b32 v254, s58, 56
	v_writelane_b32 v254, s61, 57
	v_writelane_b32 v255, s58, 2
	v_writelane_b32 v255, s61, 3
	v_writelane_b32 v254, s61, 59
	v_writelane_b32 v254, s61, 61
	v_writelane_b32 v254, s61, 63
	v_writelane_b32 v255, s61, 1
	v_writelane_b32 v255, s61, 5
	v_writelane_b32 v255, s61, 7
	s_lshl_b32 s59, s58, 19
	v_writelane_b32 v254, s59, 58
	v_writelane_b32 v254, s59, 62
	s_lshl_b32 s59, s58, 21
	v_writelane_b32 v255, s59, 4
	s_lshl_b32 s59, s60, 19
	v_writelane_b32 v254, s59, 60
	v_writelane_b32 v255, s59, 0
	s_lshl_b32 s59, s60, 21
	v_writelane_b32 v255, s59, 6
	v_writelane_b32 v255, s33, 29
	s_barrier
	s_mov_b64 s[6:7], s[10:11]
	s_branch .LBB0_455

.LBB0_848:
	s_or_b64 exec, exec, s[0:1]
	s_lshl_b32 s96, s74, 6
	s_lshl_b64 s[0:1], s[96:97], 2
	s_add_u32 s70, s40, s0
	s_addc_u32 s71, s41, s1
	s_lshl_b32 s96, s74, 9
	s_lshl_b64 s[0:1], s[96:97], 2
	v_readlane_b32 s4, v254, 29
	s_add_u32 s82, s4, s0
	v_readlane_b32 s0, v254, 30
	s_addc_u32 s83, s0, s1
	v_mov_b32_e32 v197, 0x7d0
	s_mov_b64 s[84:85], 0
	v_mov_b32_e32 v196, 0
	s_waitcnt lgkmcnt(0)
	s_barrier
	s_and_saveexec_b64 s[0:1], s[26:27]
	s_cbranch_execz .LBB0_900
	s_mov_b64 s[6:7], exec
	v_mbcnt_lo_u32_b32 v0, s6, 0
	v_mbcnt_hi_u32_b32 v0, s7, v0
	v_cmp_eq_u32_e32 vcc, 0, v0
	s_and_saveexec_b64 s[4:5], vcc
	s_cbranch_execz .LBB0_851
	s_bcnt1_i32_b64 s6, s[6:7]
	v_mov_b32_e32 v1, s6
	v_readlane_b32 s6, v255, 46
	s_and_b32 s7, s3, 7
	s_lshl_b32 s7, s7, 2
	s_cmp_lg_u32 s6, 0
	s_cselect_b32 s6, s7, 0
	v_mov_b32_e32 v2, s6
	global_atomic_add v1, v2, v1, s[70:71] offset:256 sc0
.LBB0_851:
	s_or_b64 exec, exec, s[4:5]
	s_waitcnt vmcnt(0)
	v_readfirstlane_b32 s4, v1
	v_mov_b32_e32 v196, 0
	s_nop 0
	v_add_u32_e32 v197, s4, v0
	v_readlane_b32 s4, v255, 46
	s_and_b32 s5, s3, 7
	s_lshl_b32 s5, s5, 1
	s_cmp_lg_u32 s4, 0
	s_cselect_b32 s5, s5, 0
	s_cselect_b32 s4, 2, 16
	v_cmp_gt_u32_e32 vcc, s4, v197
	v_add_u32_e32 v2, s5, v197
	v_mov_b32_e32 v4, 16
	s_nop 0
	v_cndmask_b32_e32 v197, v4, v2, vcc
	v_cmp_lt_i32_e32 vcc, 15, v197
	s_mov_b64 s[4:5], 0
	s_and_saveexec_b64 s[6:7], vcc
	s_cbranch_execz .LBB0_899
	v_mov_b32_e32 v196, 0
	s_mov_b64 s[8:9], 0
	s_branch .LBB0_855

.LBB0_854:
	s_or_b64 exec, exec, s[4:5]
	v_cmp_ne_u32_e32 vcc, s46, v197
	v_cmp_lt_i32_e64 s[4:5], 0, v196
	s_or_b64 s[4:5], vcc, s[4:5]
	s_and_b64 s[4:5], exec, s[4:5]
	s_or_b64 s[8:9], s[4:5], s[8:9]
	s_andn2_b64 exec, exec, s[8:9]
	s_cbranch_execz .LBB0_898

.LBB0_903:
	s_barrier
	s_and_saveexec_b64 s[0:1], s[26:27]
	v_mov_b32_e32 v0, s47
	ds_write_b32 v0, v197
	s_or_b64 exec, exec, s[0:1]
	v_mov_b32_e32 v0, s47
	s_waitcnt lgkmcnt(0)
	s_barrier
	ds_read_b32 v0, v0
	s_movk_i32 s0, 0x7cf
	s_waitcnt lgkmcnt(0)
	v_cmp_lt_i32_e64 s[4:5], s0, v0
	v_readfirstlane_b32 s86, v0
	s_and_b64 vcc, exec, s[4:5]
	s_cbranch_vccnz .LBB0_902
	s_and_saveexec_b64 s[0:1], s[26:27]
	s_cbranch_execz .LBB0_960
	s_xor_b64 s[10:11], s[84:85], -1
	v_mov_b32_e32 v197, 0x7d0
	s_mov_b64 s[8:9], -1
	s_and_saveexec_b64 s[6:7], s[10:11]
	s_cbranch_execz .LBB0_911
	s_mov_b64 s[10:11], exec
	v_mbcnt_lo_u32_b32 v0, s10, 0
	v_mbcnt_hi_u32_b32 v0, s11, v0
	v_cmp_eq_u32_e32 vcc, 0, v0
	s_and_saveexec_b64 s[8:9], vcc
	s_cbranch_execz .LBB0_910
	s_bcnt1_i32_b64 s10, s[10:11]
	v_mov_b32_e32 v1, s10
	v_readlane_b32 s10, v255, 46
	s_and_b32 s11, s3, 7
	s_lshl_b32 s11, s11, 2
	s_cmp_lg_u32 s10, 0
	s_cselect_b32 s10, s11, 0
	v_mov_b32_e32 v2, s10
	global_atomic_add v1, v2, v1, s[70:71] offset:256 sc0
.LBB0_910:
	s_or_b64 exec, exec, s[8:9]
	s_waitcnt vmcnt(0)
	v_readfirstlane_b32 s8, v1
	v_mov_b32_e32 v1, 0x7d0
	s_nop 0
	v_add_u32_e32 v0, s8, v0
	v_readlane_b32 s8, v255, 46
	s_and_b32 s9, s3, 7
	s_lshl_b32 s9, s9, 1
	s_cmp_lg_u32 s8, 0
	s_cselect_b32 s9, s9, 0
	s_cselect_b32 s8, 2, 16
	v_cmp_gt_u32_e32 vcc, s8, v0
	v_add_u32_e32 v2, s9, v0
	v_mov_b32_e32 v4, 16
	s_nop 0
	v_cndmask_b32_e32 v0, v4, v2, vcc
	v_cmp_lt_i32_e32 vcc, 15, v0
	s_orn2_b64 s[8:9], vcc, exec
	s_nop 0
	v_cndmask_b32_e32 v197, v0, v1, vcc
.LBB0_911:
	s_or_b64 exec, exec, s[6:7]
	v_cmp_eq_u32_e32 vcc, s46, v197
	v_cmp_gt_i32_e64 s[6:7], 1, v196
	s_and_b64 s[6:7], vcc, s[6:7]
	s_and_saveexec_b64 s[10:11], s[6:7]
	s_cbranch_execz .LBB0_959
	s_mov_b64 s[12:13], 0
	s_branch .LBB0_915

.LBB0_914:
	s_or_b64 exec, exec, s[6:7]
	v_cmp_ne_u32_e32 vcc, s46, v197
	v_cmp_lt_i32_e64 s[6:7], 0, v196
	s_or_b64 s[6:7], vcc, s[6:7]
	s_and_b64 s[6:7], exec, s[6:7]
	s_or_b64 s[12:13], s[6:7], s[12:13]
	s_andn2_b64 exec, exec, s[12:13]
	s_cbranch_execz .LBB0_958

.LBB0_1838:
	v_readlane_b32 s71, v254, 12
	s_mov_b32 s6, s71
	s_waitcnt vmcnt(0)
	s_barrier
	s_and_saveexec_b64 s[0:1], s[26:27]
	s_cbranch_execz .LBB0_1875
	v_readlane_b32 s7, v255, 17
	s_waitcnt vmcnt(0) expcnt(0) lgkmcnt(0)
	s_mov_b64 s[4:5], exec
	v_mov_b32_e32 v0, s7
	v_readlane_b32 s7, v255, 18
	ds_read_b32 v2, v0
	v_mbcnt_lo_u32_b32 v1, s4, 0
	v_mov_b32_e32 v0, s7
	ds_read_b32 v0, v0
	v_mbcnt_hi_u32_b32 v1, s5, v1
	s_lshl_b32 s20, s6, 6
	v_cmp_eq_u32_e32 vcc, 0, v1
	s_and_saveexec_b64 s[6:7], vcc
	s_cbranch_execz .LBB0_1841
	s_add_i32 s96, s20, 0x500
	v_readlane_b32 s8, v255, 46
	s_lshr_b32 s9, s20, 1
	s_add_i32 s9, s9, 0xe50
	s_cmp_lg_u32 s8, 0
	s_cselect_b32 s96, s9, s96
	s_lshl_b64 s[8:9], s[96:97], 2
	v_readlane_b32 s10, v254, 10
	v_readlane_b32 s11, v254, 11
	s_add_u32 s8, s10, s8
	s_addc_u32 s9, s11, s9
	s_bcnt1_i32_b64 s4, s[4:5]
	v_mov_b32_e32 v3, s4
	global_atomic_add v3, v65, v3, s[8:9] sc0
.LBB0_1841:
	s_or_b64 exec, exec, s[6:7]
	s_waitcnt lgkmcnt(1)
	v_cvt_f32_u32_e32 v4, v2
	s_waitcnt vmcnt(0)
	v_readfirstlane_b32 s4, v3
	buffer_inv sc1
	v_sub_u32_e32 v3, 0, v2
	v_rcp_iflag_f32_e32 v4, v4
	v_add_u32_e32 v5, s4, v1
	v_mul_f32_e32 v4, 0x4f7ffffe, v4
	v_cvt_u32_f32_e32 v4, v4
	v_mul_lo_u32 v1, v3, v4
	v_mul_hi_u32 v1, v4, v1
	v_add_u32_e32 v1, v4, v1
	v_mul_hi_u32 v1, v5, v1
	v_mul_lo_u32 v3, v1, v2
	v_sub_u32_e32 v3, v5, v3
	v_add_u32_e32 v4, 1, v1
	v_cmp_ge_u32_e32 vcc, v3, v2
	s_nop 1
	v_cndmask_b32_e32 v1, v1, v4, vcc
	v_sub_u32_e32 v4, v3, v2
	v_cndmask_b32_e32 v3, v3, v4, vcc
	v_add_u32_e32 v4, 1, v1
	v_cmp_ge_u32_e32 vcc, v3, v2
	v_add_u32_e32 v3, 1, v5
	s_nop 0
	v_cndmask_b32_e32 v1, v1, v4, vcc
	v_mul_lo_u32 v4, v2, v1
	v_add_u32_e32 v2, v4, v2
	v_cmp_ne_u32_e32 vcc, v3, v2
	s_and_saveexec_b64 s[4:5], vcc
	s_xor_b64 s[4:5], exec, s[4:5]
	s_cbranch_execz .LBB0_1855
	v_readlane_b32 s6, v255, 46
	s_cmp_lg_u32 s6, 0
	s_cbranch_scc0 .Lmy_gpoll_c
	s_lshr_b32 s96, s20, 1
	s_add_i32 s96, s96, 0xe50
	s_lshl_b64 s[6:7], s[96:97], 2
	v_readlane_b32 s8, v254, 10
	v_readlane_b32 s9, v254, 11
	s_add_u32 s8, s8, s6
	s_addc_u32 s9, s9, s7
	s_mov_b32 s21, 0
	s_waitcnt lgkmcnt(0)
.Lmy_lpoll_c:
	global_load_dword v0, v65, s[8:9] sc1
	s_waitcnt vmcnt(0)
	v_cmp_lt_u32_e32 vcc, v0, v2
	s_cbranch_vccz .LBB0_1855
	s_sleep 1
	s_add_i32 s21, s21, 1
	s_cmp_lt_u32 s21, 0x100000
	s_cbranch_scc1 .Lmy_lpoll_c
	s_branch .LBB0_1855
.Lmy_gpoll_c:
	s_add_i32 s96, s20, 0x900
	s_lshl_b64 s[6:7], s[96:97], 2
	v_readlane_b32 s8, v254, 10
	v_readlane_b32 s9, v254, 11
	s_add_u32 s8, s8, s6
	s_addc_u32 s9, s9, s7
	s_waitcnt lgkmcnt(0)
	s_nop 1
	global_load_dword v0, v65, s[8:9] sc1
	s_waitcnt vmcnt(0)
	v_cmp_eq_u32_e32 vcc, v0, v1
	s_and_saveexec_b64 s[6:7], vcc
	s_cbranch_execz .LBB0_1854
	s_mov_b32 s21, 1
	s_mov_b64 s[10:11], 0
	s_branch .LBB0_1845

.LBB0_1855:
	s_andn2_saveexec_b64 s[4:5], s[4:5]
	s_cbranch_execz .LBB0_1875
	v_readlane_b32 s4, v255, 46
	s_cmp_lg_u32 s4, 0
	s_cbranch_scc0 .Lmy_gl_c
	s_waitcnt vmcnt(0)
	s_branch .LBB0_1875

.LBB0_2079:
	s_mov_b32 s4, s71
	s_waitcnt vmcnt(0)
	s_waitcnt lgkmcnt(0)
	s_barrier
	s_and_saveexec_b64 s[6:7], s[26:27]
	s_cbranch_execz .LBB0_2116
	v_readlane_b32 s0, v255, 17
	s_waitcnt vmcnt(0) expcnt(0) lgkmcnt(0)
	s_mov_b64 s[16:17], exec
	v_mov_b32_e32 v0, s0
	v_readlane_b32 s0, v255, 18
	ds_read_b32 v2, v0
	v_mbcnt_lo_u32_b32 v1, s16, 0
	v_mov_b32_e32 v0, s0
	ds_read_b32 v0, v0
	v_mbcnt_hi_u32_b32 v1, s17, v1
	s_lshl_b32 s4, s4, 6
	v_cmp_eq_u32_e32 vcc, 0, v1
	s_and_saveexec_b64 s[18:19], vcc
	s_cbranch_execz .LBB0_2082
	s_add_i32 s96, s4, 0x500
	v_readlane_b32 s0, v255, 46
	s_lshr_b32 s1, s4, 1
	s_add_i32 s1, s1, 0xe50
	s_cmp_lg_u32 s0, 0
	s_cselect_b32 s96, s1, s96
	s_lshl_b64 s[0:1], s[96:97], 2
	v_readlane_b32 s8, v254, 10
	v_readlane_b32 s9, v254, 11
	s_add_u32 s0, s8, s0
	s_addc_u32 s1, s9, s1
	s_bcnt1_i32_b64 s5, s[16:17]
	v_mov_b32_e32 v3, s5
	global_atomic_add v3, v65, v3, s[0:1] sc0

.LBB0_2096:
	s_andn2_saveexec_b64 s[0:1], s[16:17]
	s_cbranch_execz .LBB0_2116
	v_readlane_b32 s16, v255, 46
	s_cmp_lg_u32 s16, 0
	s_cbranch_scc0 .Lmy_gl_a
	s_waitcnt vmcnt(0)
	s_branch .LBB0_2116

.LBB0_2122:
	s_add_i32 s12, s12, 1
	s_mul_i32 s0, s12, s51
	s_mul_hi_u32 s1, s12, s42
	s_add_i32 s1, s1, s0
	s_mul_i32 s0, s12, s42
	s_add_u32 s66, s0, s2
	s_addc_u32 s67, s1, s43
	v_mov_b64_e32 v[0:1], 0x300
	v_cmp_lt_i64_e64 s[6:7], s[66:67], v[0:1]
	v_mov_b64_e32 v[0:1], 0x2ff
	v_cmp_gt_i64_e32 vcc, s[66:67], v[0:1]
	s_cbranch_vccnz .LBB0_2124
	s_and_b32 s0, s66, 7
	s_lshr_b32 s1, s66, 3
	s_mul_i32 s13, s1, 43
	s_lshr_b32 s80, s13, 8
	s_mul_i32 s13, s80, 6
	s_sub_i32 s1, s1, s13
	s_lshl_b32 s13, s0, 1
	s_add_i32 s13, s13, s1
	s_lshl_b32 s0, s0, 2
	s_add_i32 s0, s0, s1
	s_add_i32 s0, s0, 14
	s_cmp_lt_u32 s1, 2
	s_cselect_b32 s82, s13, s0

.LBB0_2132:
	s_mov_b32 s4, s71
	s_waitcnt vmcnt(0)
	s_waitcnt lgkmcnt(0)
	s_barrier
	s_and_saveexec_b64 s[6:7], s[26:27]
	v_readlane_b32 s33, v255, 29
	s_cbranch_execz .LBB0_2169
	v_readlane_b32 s0, v255, 17
	s_waitcnt vmcnt(0) expcnt(0) lgkmcnt(0)
	s_mov_b64 s[18:19], exec
	v_mov_b32_e32 v0, s0
	v_readlane_b32 s0, v255, 18
	ds_read_b32 v2, v0
	v_mbcnt_lo_u32_b32 v1, s18, 0
	v_mov_b32_e32 v0, s0
	ds_read_b32 v0, v0
	v_mbcnt_hi_u32_b32 v1, s19, v1
	s_lshl_b32 s4, s4, 6
	v_cmp_eq_u32_e32 vcc, 0, v1
	s_and_saveexec_b64 s[20:21], vcc
	s_cbranch_execz .LBB0_2135
	s_add_i32 s96, s4, 0x500
	v_readlane_b32 s0, v255, 46
	s_lshr_b32 s1, s4, 1
	s_add_i32 s1, s1, 0xe50
	s_cmp_lg_u32 s0, 0
	s_cselect_b32 s96, s1, s96
	s_lshl_b64 s[0:1], s[96:97], 2
	v_readlane_b32 s8, v254, 10
	v_readlane_b32 s9, v254, 11
	s_add_u32 s0, s8, s0
	s_addc_u32 s1, s9, s1
	s_bcnt1_i32_b64 s5, s[18:19]
	v_mov_b32_e32 v3, s5
	global_atomic_add v3, v65, v3, s[0:1] sc0

.LBB0_2149:
	s_andn2_saveexec_b64 s[0:1], s[18:19]
	s_cbranch_execz .LBB0_2169
	v_readlane_b32 s18, v255, 46
	s_cmp_lg_u32 s18, 0
	s_cbranch_scc0 .Lmy_gl_b
	s_waitcnt vmcnt(0)
	s_branch .LBB0_2169
